# v40 plus scan-phase SSD recurrence loop hand-written with a 20-pair sliding window of loads and counted waits
# baseline (speedup 1.0000x reference)
.LBB0_44:
	v_ashrrev_i32_e32 v0, 9, v8
	v_and_b32_e32 v6, 0xffffffc0, v0
	v_ashrrev_i32_e32 v7, 31, v6
	v_bfe_u32 v9, v8, 13, 2
	v_lshlrev_b64 v[2:3], 2, v[6:7]
	v_or_b32_e32 v2, v2, v9
	v_and_b32_e32 v10, 0x1fff, v8
	v_lshlrev_b64 v[4:5], 15, v[2:3]
	v_lshl_add_u64 v[4:5], s[30:31], 0, v[4:5]
	v_lshlrev_b32_e32 v0, 2, v10
	v_lshlrev_b64 v[2:3], 14, v[2:3]
	v_lshl_add_u64 v[4:5], v[4:5], 0, v[0:1]
	v_lshl_add_u64 v[2:3], s[6:7], 0, v[2:3]
	v_lshlrev_b32_e32 v0, 1, v10
	v_lshl_add_u64 v[2:3], v[2:3], 0, v[0:1]
	v_lshl_add_u64 v[6:7], v[6:7], 4, s[84:85]
	v_lshlrev_b32_e32 v0, 2, v9
	v_lshl_add_u64 v[6:7], v[6:7], 0, v[0:1]
	v_add_u32_e32 v8, s3, v8
	v_mov_b32_e32 v10, v4
	v_mov_b32_e32 v11, v5
	v_mov_b32_e32 v12, v2
	v_mov_b32_e32 v13, v3
	v_mov_b32_e32 v116, 0
	global_load_dword v76, v[10:11], off
	global_load_dword v96, v[6:7], off offset:0
	v_add_co_u32_e32 v10, vcc, 0x20000, v10
	s_nop 1
	v_addc_co_u32_e32 v11, vcc, 0, v11, vcc
	global_load_dword v77, v[10:11], off
	global_load_dword v97, v[6:7], off offset:16
	v_add_co_u32_e32 v10, vcc, 0x20000, v10
	s_nop 1
	v_addc_co_u32_e32 v11, vcc, 0, v11, vcc
	global_load_dword v78, v[10:11], off
	global_load_dword v98, v[6:7], off offset:32
	v_add_co_u32_e32 v10, vcc, 0x20000, v10
	s_nop 1
	v_addc_co_u32_e32 v11, vcc, 0, v11, vcc
	global_load_dword v79, v[10:11], off
	global_load_dword v99, v[6:7], off offset:48
	v_add_co_u32_e32 v10, vcc, 0x20000, v10
	s_nop 1
	v_addc_co_u32_e32 v11, vcc, 0, v11, vcc
	global_load_dword v80, v[10:11], off
	global_load_dword v100, v[6:7], off offset:64
	v_add_co_u32_e32 v10, vcc, 0x20000, v10
	s_nop 1
	v_addc_co_u32_e32 v11, vcc, 0, v11, vcc
	global_load_dword v81, v[10:11], off
	global_load_dword v101, v[6:7], off offset:80
	v_add_co_u32_e32 v10, vcc, 0x20000, v10
	s_nop 1
	v_addc_co_u32_e32 v11, vcc, 0, v11, vcc
	global_load_dword v82, v[10:11], off
	global_load_dword v102, v[6:7], off offset:96
	v_add_co_u32_e32 v10, vcc, 0x20000, v10
	s_nop 1
	v_addc_co_u32_e32 v11, vcc, 0, v11, vcc
	global_load_dword v83, v[10:11], off
	global_load_dword v103, v[6:7], off offset:112
	v_add_co_u32_e32 v10, vcc, 0x20000, v10
	s_nop 1
	v_addc_co_u32_e32 v11, vcc, 0, v11, vcc
	global_load_dword v84, v[10:11], off
	global_load_dword v104, v[6:7], off offset:128
	v_add_co_u32_e32 v10, vcc, 0x20000, v10
	s_nop 1
	v_addc_co_u32_e32 v11, vcc, 0, v11, vcc
	global_load_dword v85, v[10:11], off
	global_load_dword v105, v[6:7], off offset:144
	v_add_co_u32_e32 v10, vcc, 0x20000, v10
	s_nop 1
	v_addc_co_u32_e32 v11, vcc, 0, v11, vcc
	global_load_dword v86, v[10:11], off
	global_load_dword v106, v[6:7], off offset:160
	v_add_co_u32_e32 v10, vcc, 0x20000, v10
	s_nop 1
	v_addc_co_u32_e32 v11, vcc, 0, v11, vcc
	global_load_dword v87, v[10:11], off
	global_load_dword v107, v[6:7], off offset:176
	v_add_co_u32_e32 v10, vcc, 0x20000, v10
	s_nop 1
	v_addc_co_u32_e32 v11, vcc, 0, v11, vcc
	global_load_dword v88, v[10:11], off
	global_load_dword v108, v[6:7], off offset:192
	v_add_co_u32_e32 v10, vcc, 0x20000, v10
	s_nop 1
	v_addc_co_u32_e32 v11, vcc, 0, v11, vcc
	global_load_dword v89, v[10:11], off
	global_load_dword v109, v[6:7], off offset:208
	v_add_co_u32_e32 v10, vcc, 0x20000, v10
	s_nop 1
	v_addc_co_u32_e32 v11, vcc, 0, v11, vcc
	global_load_dword v90, v[10:11], off
	global_load_dword v110, v[6:7], off offset:224
	v_add_co_u32_e32 v10, vcc, 0x20000, v10
	s_nop 1
	v_addc_co_u32_e32 v11, vcc, 0, v11, vcc
	global_load_dword v91, v[10:11], off
	global_load_dword v111, v[6:7], off offset:240
	v_add_co_u32_e32 v10, vcc, 0x20000, v10
	s_nop 1
	v_addc_co_u32_e32 v11, vcc, 0, v11, vcc
	global_load_dword v92, v[10:11], off
	global_load_dword v112, v[6:7], off offset:256
	v_add_co_u32_e32 v10, vcc, 0x20000, v10
	s_nop 1
	v_addc_co_u32_e32 v11, vcc, 0, v11, vcc
	global_load_dword v93, v[10:11], off
	global_load_dword v113, v[6:7], off offset:272
	v_add_co_u32_e32 v10, vcc, 0x20000, v10
	s_nop 1
	v_addc_co_u32_e32 v11, vcc, 0, v11, vcc
	global_load_dword v94, v[10:11], off
	global_load_dword v114, v[6:7], off offset:288
	v_add_co_u32_e32 v10, vcc, 0x20000, v10
	s_nop 1
	v_addc_co_u32_e32 v11, vcc, 0, v11, vcc
	global_load_dword v95, v[10:11], off
	global_load_dword v115, v[6:7], off offset:304
	v_add_co_u32_e32 v10, vcc, 0x20000, v10
	s_nop 1
	v_addc_co_u32_e32 v11, vcc, 0, v11, vcc
	v_cvt_pk_bf16_f32 v0, v116, s0
	global_store_short v[12:13], v0, off
	v_add_co_u32_e32 v12, vcc, 0x10000, v12
	s_waitcnt vmcnt(39)
	s_nop 0
	v_addc_co_u32_e32 v13, vcc, 0, v13, vcc
	v_fma_f32 v116, v116, v96, v76
	global_load_dword v76, v[10:11], off
	global_load_dword v96, v[6:7], off offset:320
	v_add_co_u32_e32 v10, vcc, 0x20000, v10
	s_nop 1
	v_addc_co_u32_e32 v11, vcc, 0, v11, vcc
	v_cvt_pk_bf16_f32 v0, v116, s0
	global_store_short v[12:13], v0, off
	v_add_co_u32_e32 v12, vcc, 0x10000, v12
	s_waitcnt vmcnt(40)
	s_nop 0
	v_addc_co_u32_e32 v13, vcc, 0, v13, vcc
	v_fma_f32 v116, v116, v97, v77
	global_load_dword v77, v[10:11], off
	global_load_dword v97, v[6:7], off offset:336
	v_add_co_u32_e32 v10, vcc, 0x20000, v10
	s_nop 1
	v_addc_co_u32_e32 v11, vcc, 0, v11, vcc
	v_cvt_pk_bf16_f32 v0, v116, s0
	global_store_short v[12:13], v0, off
	v_add_co_u32_e32 v12, vcc, 0x10000, v12
	s_waitcnt vmcnt(41)
	s_nop 0
	v_addc_co_u32_e32 v13, vcc, 0, v13, vcc
	v_fma_f32 v116, v116, v98, v78
	global_load_dword v78, v[10:11], off
	global_load_dword v98, v[6:7], off offset:352
	v_add_co_u32_e32 v10, vcc, 0x20000, v10
	s_nop 1
	v_addc_co_u32_e32 v11, vcc, 0, v11, vcc
	v_cvt_pk_bf16_f32 v0, v116, s0
	global_store_short v[12:13], v0, off
	v_add_co_u32_e32 v12, vcc, 0x10000, v12
	s_waitcnt vmcnt(42)
	s_nop 0
	v_addc_co_u32_e32 v13, vcc, 0, v13, vcc
	v_fma_f32 v116, v116, v99, v79
	global_load_dword v79, v[10:11], off
	global_load_dword v99, v[6:7], off offset:368
	v_add_co_u32_e32 v10, vcc, 0x20000, v10
	s_nop 1
	v_addc_co_u32_e32 v11, vcc, 0, v11, vcc
	v_cvt_pk_bf16_f32 v0, v116, s0
	global_store_short v[12:13], v0, off
	v_add_co_u32_e32 v12, vcc, 0x10000, v12
	s_waitcnt vmcnt(43)
	s_nop 0
	v_addc_co_u32_e32 v13, vcc, 0, v13, vcc
	v_fma_f32 v116, v116, v100, v80
	global_load_dword v80, v[10:11], off
	global_load_dword v100, v[6:7], off offset:384
	v_add_co_u32_e32 v10, vcc, 0x20000, v10
	s_nop 1
	v_addc_co_u32_e32 v11, vcc, 0, v11, vcc
	v_cvt_pk_bf16_f32 v0, v116, s0
	global_store_short v[12:13], v0, off
	v_add_co_u32_e32 v12, vcc, 0x10000, v12
	s_waitcnt vmcnt(44)
	s_nop 0
	v_addc_co_u32_e32 v13, vcc, 0, v13, vcc
	v_fma_f32 v116, v116, v101, v81
	global_load_dword v81, v[10:11], off
	global_load_dword v101, v[6:7], off offset:400
	v_add_co_u32_e32 v10, vcc, 0x20000, v10
	s_nop 1
	v_addc_co_u32_e32 v11, vcc, 0, v11, vcc
	v_cvt_pk_bf16_f32 v0, v116, s0
	global_store_short v[12:13], v0, off
	v_add_co_u32_e32 v12, vcc, 0x10000, v12
	s_waitcnt vmcnt(45)
	s_nop 0
	v_addc_co_u32_e32 v13, vcc, 0, v13, vcc
	v_fma_f32 v116, v116, v102, v82
	global_load_dword v82, v[10:11], off
	global_load_dword v102, v[6:7], off offset:416
	v_add_co_u32_e32 v10, vcc, 0x20000, v10
	s_nop 1
	v_addc_co_u32_e32 v11, vcc, 0, v11, vcc
	v_cvt_pk_bf16_f32 v0, v116, s0
	global_store_short v[12:13], v0, off
	v_add_co_u32_e32 v12, vcc, 0x10000, v12
	s_waitcnt vmcnt(46)
	s_nop 0
	v_addc_co_u32_e32 v13, vcc, 0, v13, vcc
	v_fma_f32 v116, v116, v103, v83
	global_load_dword v83, v[10:11], off
	global_load_dword v103, v[6:7], off offset:432
	v_add_co_u32_e32 v10, vcc, 0x20000, v10
	s_nop 1
	v_addc_co_u32_e32 v11, vcc, 0, v11, vcc
	v_cvt_pk_bf16_f32 v0, v116, s0
	global_store_short v[12:13], v0, off
	v_add_co_u32_e32 v12, vcc, 0x10000, v12
	s_waitcnt vmcnt(47)
	s_nop 0
	v_addc_co_u32_e32 v13, vcc, 0, v13, vcc
	v_fma_f32 v116, v116, v104, v84
	global_load_dword v84, v[10:11], off
	global_load_dword v104, v[6:7], off offset:448
	v_add_co_u32_e32 v10, vcc, 0x20000, v10
	s_nop 1
	v_addc_co_u32_e32 v11, vcc, 0, v11, vcc
	v_cvt_pk_bf16_f32 v0, v116, s0
	global_store_short v[12:13], v0, off
	v_add_co_u32_e32 v12, vcc, 0x10000, v12
	s_waitcnt vmcnt(48)
	s_nop 0
	v_addc_co_u32_e32 v13, vcc, 0, v13, vcc
	v_fma_f32 v116, v116, v105, v85
	global_load_dword v85, v[10:11], off
	global_load_dword v105, v[6:7], off offset:464
	v_add_co_u32_e32 v10, vcc, 0x20000, v10
	s_nop 1
	v_addc_co_u32_e32 v11, vcc, 0, v11, vcc
	v_cvt_pk_bf16_f32 v0, v116, s0
	global_store_short v[12:13], v0, off
	v_add_co_u32_e32 v12, vcc, 0x10000, v12
	s_waitcnt vmcnt(49)
	s_nop 0
	v_addc_co_u32_e32 v13, vcc, 0, v13, vcc
	v_fma_f32 v116, v116, v106, v86
	global_load_dword v86, v[10:11], off
	global_load_dword v106, v[6:7], off offset:480
	v_add_co_u32_e32 v10, vcc, 0x20000, v10
	s_nop 1
	v_addc_co_u32_e32 v11, vcc, 0, v11, vcc
	v_cvt_pk_bf16_f32 v0, v116, s0
	global_store_short v[12:13], v0, off
	v_add_co_u32_e32 v12, vcc, 0x10000, v12
	s_waitcnt vmcnt(50)
	s_nop 0
	v_addc_co_u32_e32 v13, vcc, 0, v13, vcc
	v_fma_f32 v116, v116, v107, v87
	global_load_dword v87, v[10:11], off
	global_load_dword v107, v[6:7], off offset:496
	v_add_co_u32_e32 v10, vcc, 0x20000, v10
	s_nop 1
	v_addc_co_u32_e32 v11, vcc, 0, v11, vcc
	v_cvt_pk_bf16_f32 v0, v116, s0
	global_store_short v[12:13], v0, off
	v_add_co_u32_e32 v12, vcc, 0x10000, v12
	s_waitcnt vmcnt(51)
	s_nop 0
	v_addc_co_u32_e32 v13, vcc, 0, v13, vcc
	v_fma_f32 v116, v116, v108, v88
	global_load_dword v88, v[10:11], off
	global_load_dword v108, v[6:7], off offset:512
	v_add_co_u32_e32 v10, vcc, 0x20000, v10
	s_nop 1
	v_addc_co_u32_e32 v11, vcc, 0, v11, vcc
	v_cvt_pk_bf16_f32 v0, v116, s0
	global_store_short v[12:13], v0, off
	v_add_co_u32_e32 v12, vcc, 0x10000, v12
	s_waitcnt vmcnt(52)
	s_nop 0
	v_addc_co_u32_e32 v13, vcc, 0, v13, vcc
	v_fma_f32 v116, v116, v109, v89
	global_load_dword v89, v[10:11], off
	global_load_dword v109, v[6:7], off offset:528
	v_add_co_u32_e32 v10, vcc, 0x20000, v10
	s_nop 1
	v_addc_co_u32_e32 v11, vcc, 0, v11, vcc
	v_cvt_pk_bf16_f32 v0, v116, s0
	global_store_short v[12:13], v0, off
	v_add_co_u32_e32 v12, vcc, 0x10000, v12
	s_waitcnt vmcnt(53)
	s_nop 0
	v_addc_co_u32_e32 v13, vcc, 0, v13, vcc
	v_fma_f32 v116, v116, v110, v90
	global_load_dword v90, v[10:11], off
	global_load_dword v110, v[6:7], off offset:544
	v_add_co_u32_e32 v10, vcc, 0x20000, v10
	s_nop 1
	v_addc_co_u32_e32 v11, vcc, 0, v11, vcc
	v_cvt_pk_bf16_f32 v0, v116, s0
	global_store_short v[12:13], v0, off
	v_add_co_u32_e32 v12, vcc, 0x10000, v12
	s_waitcnt vmcnt(54)
	s_nop 0
	v_addc_co_u32_e32 v13, vcc, 0, v13, vcc
	v_fma_f32 v116, v116, v111, v91
	global_load_dword v91, v[10:11], off
	global_load_dword v111, v[6:7], off offset:560
	v_add_co_u32_e32 v10, vcc, 0x20000, v10
	s_nop 1
	v_addc_co_u32_e32 v11, vcc, 0, v11, vcc
	v_cvt_pk_bf16_f32 v0, v116, s0
	global_store_short v[12:13], v0, off
	v_add_co_u32_e32 v12, vcc, 0x10000, v12
	s_waitcnt vmcnt(55)
	s_nop 0
	v_addc_co_u32_e32 v13, vcc, 0, v13, vcc
	v_fma_f32 v116, v116, v112, v92
	global_load_dword v92, v[10:11], off
	global_load_dword v112, v[6:7], off offset:576
	v_add_co_u32_e32 v10, vcc, 0x20000, v10
	s_nop 1
	v_addc_co_u32_e32 v11, vcc, 0, v11, vcc
	v_cvt_pk_bf16_f32 v0, v116, s0
	global_store_short v[12:13], v0, off
	v_add_co_u32_e32 v12, vcc, 0x10000, v12
	s_waitcnt vmcnt(56)
	s_nop 0
	v_addc_co_u32_e32 v13, vcc, 0, v13, vcc
	v_fma_f32 v116, v116, v113, v93
	global_load_dword v93, v[10:11], off
	global_load_dword v113, v[6:7], off offset:592
	v_add_co_u32_e32 v10, vcc, 0x20000, v10
	s_nop 1
	v_addc_co_u32_e32 v11, vcc, 0, v11, vcc
	v_cvt_pk_bf16_f32 v0, v116, s0
	global_store_short v[12:13], v0, off
	v_add_co_u32_e32 v12, vcc, 0x10000, v12
	s_waitcnt vmcnt(57)
	s_nop 0
	v_addc_co_u32_e32 v13, vcc, 0, v13, vcc
	v_fma_f32 v116, v116, v114, v94
	global_load_dword v94, v[10:11], off
	global_load_dword v114, v[6:7], off offset:608
	v_add_co_u32_e32 v10, vcc, 0x20000, v10
	s_nop 1
	v_addc_co_u32_e32 v11, vcc, 0, v11, vcc
	v_cvt_pk_bf16_f32 v0, v116, s0
	global_store_short v[12:13], v0, off
	v_add_co_u32_e32 v12, vcc, 0x10000, v12
	s_waitcnt vmcnt(58)
	s_nop 0
	v_addc_co_u32_e32 v13, vcc, 0, v13, vcc
	v_fma_f32 v116, v116, v115, v95
	global_load_dword v95, v[10:11], off
	global_load_dword v115, v[6:7], off offset:624
	v_add_co_u32_e32 v10, vcc, 0x20000, v10
	s_nop 1
	v_addc_co_u32_e32 v11, vcc, 0, v11, vcc
	v_cvt_pk_bf16_f32 v0, v116, s0
	global_store_short v[12:13], v0, off
	v_add_co_u32_e32 v12, vcc, 0x10000, v12
	s_waitcnt vmcnt(58)
	s_nop 0
	v_addc_co_u32_e32 v13, vcc, 0, v13, vcc
	v_fma_f32 v116, v116, v96, v76
	global_load_dword v76, v[10:11], off
	global_load_dword v96, v[6:7], off offset:640
	v_add_co_u32_e32 v10, vcc, 0x20000, v10
	s_nop 1
	v_addc_co_u32_e32 v11, vcc, 0, v11, vcc
	v_cvt_pk_bf16_f32 v0, v116, s0
	global_store_short v[12:13], v0, off
	v_add_co_u32_e32 v12, vcc, 0x10000, v12
	s_waitcnt vmcnt(58)
	s_nop 0
	v_addc_co_u32_e32 v13, vcc, 0, v13, vcc
	v_fma_f32 v116, v116, v97, v77
	global_load_dword v77, v[10:11], off
	global_load_dword v97, v[6:7], off offset:656
	v_add_co_u32_e32 v10, vcc, 0x20000, v10
	s_nop 1
	v_addc_co_u32_e32 v11, vcc, 0, v11, vcc
	v_cvt_pk_bf16_f32 v0, v116, s0
	global_store_short v[12:13], v0, off
	v_add_co_u32_e32 v12, vcc, 0x10000, v12
	s_waitcnt vmcnt(58)
	s_nop 0
	v_addc_co_u32_e32 v13, vcc, 0, v13, vcc
	v_fma_f32 v116, v116, v98, v78
	global_load_dword v78, v[10:11], off
	global_load_dword v98, v[6:7], off offset:672
	v_add_co_u32_e32 v10, vcc, 0x20000, v10
	s_nop 1
	v_addc_co_u32_e32 v11, vcc, 0, v11, vcc
	v_cvt_pk_bf16_f32 v0, v116, s0
	global_store_short v[12:13], v0, off
	v_add_co_u32_e32 v12, vcc, 0x10000, v12
	s_waitcnt vmcnt(58)
	s_nop 0
	v_addc_co_u32_e32 v13, vcc, 0, v13, vcc
	v_fma_f32 v116, v116, v99, v79
	global_load_dword v79, v[10:11], off
	global_load_dword v99, v[6:7], off offset:688
	v_add_co_u32_e32 v10, vcc, 0x20000, v10
	s_nop 1
	v_addc_co_u32_e32 v11, vcc, 0, v11, vcc
	v_cvt_pk_bf16_f32 v0, v116, s0
	global_store_short v[12:13], v0, off
	v_add_co_u32_e32 v12, vcc, 0x10000, v12
	s_waitcnt vmcnt(58)
	s_nop 0
	v_addc_co_u32_e32 v13, vcc, 0, v13, vcc
	v_fma_f32 v116, v116, v100, v80
	global_load_dword v80, v[10:11], off
	global_load_dword v100, v[6:7], off offset:704
	v_add_co_u32_e32 v10, vcc, 0x20000, v10
	s_nop 1
	v_addc_co_u32_e32 v11, vcc, 0, v11, vcc
	v_cvt_pk_bf16_f32 v0, v116, s0
	global_store_short v[12:13], v0, off
	v_add_co_u32_e32 v12, vcc, 0x10000, v12
	s_waitcnt vmcnt(58)
	s_nop 0
	v_addc_co_u32_e32 v13, vcc, 0, v13, vcc
	v_fma_f32 v116, v116, v101, v81
	global_load_dword v81, v[10:11], off
	global_load_dword v101, v[6:7], off offset:720
	v_add_co_u32_e32 v10, vcc, 0x20000, v10
	s_nop 1
	v_addc_co_u32_e32 v11, vcc, 0, v11, vcc
	v_cvt_pk_bf16_f32 v0, v116, s0
	global_store_short v[12:13], v0, off
	v_add_co_u32_e32 v12, vcc, 0x10000, v12
	s_waitcnt vmcnt(58)
	s_nop 0
	v_addc_co_u32_e32 v13, vcc, 0, v13, vcc
	v_fma_f32 v116, v116, v102, v82
	global_load_dword v82, v[10:11], off
	global_load_dword v102, v[6:7], off offset:736
	v_add_co_u32_e32 v10, vcc, 0x20000, v10
	s_nop 1
	v_addc_co_u32_e32 v11, vcc, 0, v11, vcc
	v_cvt_pk_bf16_f32 v0, v116, s0
	global_store_short v[12:13], v0, off
	v_add_co_u32_e32 v12, vcc, 0x10000, v12
	s_waitcnt vmcnt(58)
	s_nop 0
	v_addc_co_u32_e32 v13, vcc, 0, v13, vcc
	v_fma_f32 v116, v116, v103, v83
	global_load_dword v83, v[10:11], off
	global_load_dword v103, v[6:7], off offset:752
	v_add_co_u32_e32 v10, vcc, 0x20000, v10
	s_nop 1
	v_addc_co_u32_e32 v11, vcc, 0, v11, vcc
	v_cvt_pk_bf16_f32 v0, v116, s0
	global_store_short v[12:13], v0, off
	v_add_co_u32_e32 v12, vcc, 0x10000, v12
	s_waitcnt vmcnt(58)
	s_nop 0
	v_addc_co_u32_e32 v13, vcc, 0, v13, vcc
	v_fma_f32 v116, v116, v104, v84
	global_load_dword v84, v[10:11], off
	global_load_dword v104, v[6:7], off offset:768
	v_add_co_u32_e32 v10, vcc, 0x20000, v10
	s_nop 1
	v_addc_co_u32_e32 v11, vcc, 0, v11, vcc
	v_cvt_pk_bf16_f32 v0, v116, s0
	global_store_short v[12:13], v0, off
	v_add_co_u32_e32 v12, vcc, 0x10000, v12
	s_waitcnt vmcnt(58)
	s_nop 0
	v_addc_co_u32_e32 v13, vcc, 0, v13, vcc
	v_fma_f32 v116, v116, v105, v85
	global_load_dword v85, v[10:11], off
	global_load_dword v105, v[6:7], off offset:784
	v_add_co_u32_e32 v10, vcc, 0x20000, v10
	s_nop 1
	v_addc_co_u32_e32 v11, vcc, 0, v11, vcc
	v_cvt_pk_bf16_f32 v0, v116, s0
	global_store_short v[12:13], v0, off
	v_add_co_u32_e32 v12, vcc, 0x10000, v12
	s_waitcnt vmcnt(58)
	s_nop 0
	v_addc_co_u32_e32 v13, vcc, 0, v13, vcc
	v_fma_f32 v116, v116, v106, v86
	global_load_dword v86, v[10:11], off
	global_load_dword v106, v[6:7], off offset:800
	v_add_co_u32_e32 v10, vcc, 0x20000, v10
	s_nop 1
	v_addc_co_u32_e32 v11, vcc, 0, v11, vcc
	v_cvt_pk_bf16_f32 v0, v116, s0
	global_store_short v[12:13], v0, off
	v_add_co_u32_e32 v12, vcc, 0x10000, v12
	s_waitcnt vmcnt(58)
	s_nop 0
	v_addc_co_u32_e32 v13, vcc, 0, v13, vcc
	v_fma_f32 v116, v116, v107, v87
	global_load_dword v87, v[10:11], off
	global_load_dword v107, v[6:7], off offset:816
	v_add_co_u32_e32 v10, vcc, 0x20000, v10
	s_nop 1
	v_addc_co_u32_e32 v11, vcc, 0, v11, vcc
	v_cvt_pk_bf16_f32 v0, v116, s0
	global_store_short v[12:13], v0, off
	v_add_co_u32_e32 v12, vcc, 0x10000, v12
	s_waitcnt vmcnt(58)
	s_nop 0
	v_addc_co_u32_e32 v13, vcc, 0, v13, vcc
	v_fma_f32 v116, v116, v108, v88
	global_load_dword v88, v[10:11], off
	global_load_dword v108, v[6:7], off offset:832
	v_add_co_u32_e32 v10, vcc, 0x20000, v10
	s_nop 1
	v_addc_co_u32_e32 v11, vcc, 0, v11, vcc
	v_cvt_pk_bf16_f32 v0, v116, s0
	global_store_short v[12:13], v0, off
	v_add_co_u32_e32 v12, vcc, 0x10000, v12
	s_waitcnt vmcnt(58)
	s_nop 0
	v_addc_co_u32_e32 v13, vcc, 0, v13, vcc
	v_fma_f32 v116, v116, v109, v89
	global_load_dword v89, v[10:11], off
	global_load_dword v109, v[6:7], off offset:848
	v_add_co_u32_e32 v10, vcc, 0x20000, v10
	s_nop 1
	v_addc_co_u32_e32 v11, vcc, 0, v11, vcc
	v_cvt_pk_bf16_f32 v0, v116, s0
	global_store_short v[12:13], v0, off
	v_add_co_u32_e32 v12, vcc, 0x10000, v12
	s_waitcnt vmcnt(58)
	s_nop 0
	v_addc_co_u32_e32 v13, vcc, 0, v13, vcc
	v_fma_f32 v116, v116, v110, v90
	global_load_dword v90, v[10:11], off
	global_load_dword v110, v[6:7], off offset:864
	v_add_co_u32_e32 v10, vcc, 0x20000, v10
	s_nop 1
	v_addc_co_u32_e32 v11, vcc, 0, v11, vcc
	v_cvt_pk_bf16_f32 v0, v116, s0
	global_store_short v[12:13], v0, off
	v_add_co_u32_e32 v12, vcc, 0x10000, v12
	s_waitcnt vmcnt(58)
	s_nop 0
	v_addc_co_u32_e32 v13, vcc, 0, v13, vcc
	v_fma_f32 v116, v116, v111, v91
	global_load_dword v91, v[10:11], off
	global_load_dword v111, v[6:7], off offset:880
	v_add_co_u32_e32 v10, vcc, 0x20000, v10
	s_nop 1
	v_addc_co_u32_e32 v11, vcc, 0, v11, vcc
	v_cvt_pk_bf16_f32 v0, v116, s0
	global_store_short v[12:13], v0, off
	v_add_co_u32_e32 v12, vcc, 0x10000, v12
	s_waitcnt vmcnt(58)
	s_nop 0
	v_addc_co_u32_e32 v13, vcc, 0, v13, vcc
	v_fma_f32 v116, v116, v112, v92
	global_load_dword v92, v[10:11], off
	global_load_dword v112, v[6:7], off offset:896
	v_add_co_u32_e32 v10, vcc, 0x20000, v10
	s_nop 1
	v_addc_co_u32_e32 v11, vcc, 0, v11, vcc
	v_cvt_pk_bf16_f32 v0, v116, s0
	global_store_short v[12:13], v0, off
	v_add_co_u32_e32 v12, vcc, 0x10000, v12
	s_waitcnt vmcnt(58)
	s_nop 0
	v_addc_co_u32_e32 v13, vcc, 0, v13, vcc
	v_fma_f32 v116, v116, v113, v93
	global_load_dword v93, v[10:11], off
	global_load_dword v113, v[6:7], off offset:912
	v_add_co_u32_e32 v10, vcc, 0x20000, v10
	s_nop 1
	v_addc_co_u32_e32 v11, vcc, 0, v11, vcc
	v_cvt_pk_bf16_f32 v0, v116, s0
	global_store_short v[12:13], v0, off
	v_add_co_u32_e32 v12, vcc, 0x10000, v12
	s_waitcnt vmcnt(58)
	s_nop 0
	v_addc_co_u32_e32 v13, vcc, 0, v13, vcc
	v_fma_f32 v116, v116, v114, v94
	global_load_dword v94, v[10:11], off
	global_load_dword v114, v[6:7], off offset:928
	v_add_co_u32_e32 v10, vcc, 0x20000, v10
	s_nop 1
	v_addc_co_u32_e32 v11, vcc, 0, v11, vcc
	v_cvt_pk_bf16_f32 v0, v116, s0
	global_store_short v[12:13], v0, off
	v_add_co_u32_e32 v12, vcc, 0x10000, v12
	s_waitcnt vmcnt(58)
	s_nop 0
	v_addc_co_u32_e32 v13, vcc, 0, v13, vcc
	v_fma_f32 v116, v116, v115, v95
	global_load_dword v95, v[10:11], off
	global_load_dword v115, v[6:7], off offset:944
	v_add_co_u32_e32 v10, vcc, 0x20000, v10
	s_nop 1
	v_addc_co_u32_e32 v11, vcc, 0, v11, vcc
	v_cvt_pk_bf16_f32 v0, v116, s0
	global_store_short v[12:13], v0, off
	v_add_co_u32_e32 v12, vcc, 0x10000, v12
	s_waitcnt vmcnt(58)
	s_nop 0
	v_addc_co_u32_e32 v13, vcc, 0, v13, vcc
	v_fma_f32 v116, v116, v96, v76
	global_load_dword v76, v[10:11], off
	global_load_dword v96, v[6:7], off offset:960
	v_add_co_u32_e32 v10, vcc, 0x20000, v10
	s_nop 1
	v_addc_co_u32_e32 v11, vcc, 0, v11, vcc
	v_cvt_pk_bf16_f32 v0, v116, s0
	global_store_short v[12:13], v0, off
	v_add_co_u32_e32 v12, vcc, 0x10000, v12
	s_waitcnt vmcnt(58)
	s_nop 0
	v_addc_co_u32_e32 v13, vcc, 0, v13, vcc
	v_fma_f32 v116, v116, v97, v77
	global_load_dword v77, v[10:11], off
	global_load_dword v97, v[6:7], off offset:976
	v_add_co_u32_e32 v10, vcc, 0x20000, v10
	s_nop 1
	v_addc_co_u32_e32 v11, vcc, 0, v11, vcc
	v_cvt_pk_bf16_f32 v0, v116, s0
	global_store_short v[12:13], v0, off
	v_add_co_u32_e32 v12, vcc, 0x10000, v12
	s_waitcnt vmcnt(58)
	s_nop 0
	v_addc_co_u32_e32 v13, vcc, 0, v13, vcc
	v_fma_f32 v116, v116, v98, v78
	global_load_dword v78, v[10:11], off
	global_load_dword v98, v[6:7], off offset:992
	v_add_co_u32_e32 v10, vcc, 0x20000, v10
	s_nop 1
	v_addc_co_u32_e32 v11, vcc, 0, v11, vcc
	v_cvt_pk_bf16_f32 v0, v116, s0
	global_store_short v[12:13], v0, off
	v_add_co_u32_e32 v12, vcc, 0x10000, v12
	s_waitcnt vmcnt(58)
	s_nop 0
	v_addc_co_u32_e32 v13, vcc, 0, v13, vcc
	v_fma_f32 v116, v116, v99, v79
	global_load_dword v79, v[10:11], off
	global_load_dword v99, v[6:7], off offset:1008
	v_add_co_u32_e32 v10, vcc, 0x20000, v10
	s_nop 1
	v_addc_co_u32_e32 v11, vcc, 0, v11, vcc
	v_cvt_pk_bf16_f32 v0, v116, s0
	global_store_short v[12:13], v0, off
	v_add_co_u32_e32 v12, vcc, 0x10000, v12
	s_waitcnt vmcnt(58)
	s_nop 0
	v_addc_co_u32_e32 v13, vcc, 0, v13, vcc
	v_fma_f32 v116, v116, v100, v80
	v_cvt_pk_bf16_f32 v0, v116, s0
	global_store_short v[12:13], v0, off
	v_add_co_u32_e32 v12, vcc, 0x10000, v12
	s_waitcnt vmcnt(56)
	s_nop 0
	v_addc_co_u32_e32 v13, vcc, 0, v13, vcc
	v_fma_f32 v116, v116, v101, v81
	v_cvt_pk_bf16_f32 v0, v116, s0
	global_store_short v[12:13], v0, off
	v_add_co_u32_e32 v12, vcc, 0x10000, v12
	s_waitcnt vmcnt(54)
	s_nop 0
	v_addc_co_u32_e32 v13, vcc, 0, v13, vcc
	v_fma_f32 v116, v116, v102, v82
	v_cvt_pk_bf16_f32 v0, v116, s0
	global_store_short v[12:13], v0, off
	v_add_co_u32_e32 v12, vcc, 0x10000, v12
	s_waitcnt vmcnt(52)
	s_nop 0
	v_addc_co_u32_e32 v13, vcc, 0, v13, vcc
	v_fma_f32 v116, v116, v103, v83
	v_cvt_pk_bf16_f32 v0, v116, s0
	global_store_short v[12:13], v0, off
	v_add_co_u32_e32 v12, vcc, 0x10000, v12
	s_waitcnt vmcnt(50)
	s_nop 0
	v_addc_co_u32_e32 v13, vcc, 0, v13, vcc
	v_fma_f32 v116, v116, v104, v84
	v_cvt_pk_bf16_f32 v0, v116, s0
	global_store_short v[12:13], v0, off
	v_add_co_u32_e32 v12, vcc, 0x10000, v12
	s_waitcnt vmcnt(48)
	s_nop 0
	v_addc_co_u32_e32 v13, vcc, 0, v13, vcc
	v_fma_f32 v116, v116, v105, v85
	v_cvt_pk_bf16_f32 v0, v116, s0
	global_store_short v[12:13], v0, off
	v_add_co_u32_e32 v12, vcc, 0x10000, v12
	s_waitcnt vmcnt(46)
	s_nop 0
	v_addc_co_u32_e32 v13, vcc, 0, v13, vcc
	v_fma_f32 v116, v116, v106, v86
	v_cvt_pk_bf16_f32 v0, v116, s0
	global_store_short v[12:13], v0, off
	v_add_co_u32_e32 v12, vcc, 0x10000, v12
	s_waitcnt vmcnt(44)
	s_nop 0
	v_addc_co_u32_e32 v13, vcc, 0, v13, vcc
	v_fma_f32 v116, v116, v107, v87
	v_cvt_pk_bf16_f32 v0, v116, s0
	global_store_short v[12:13], v0, off
	v_add_co_u32_e32 v12, vcc, 0x10000, v12
	s_waitcnt vmcnt(42)
	s_nop 0
	v_addc_co_u32_e32 v13, vcc, 0, v13, vcc
	v_fma_f32 v116, v116, v108, v88
	v_cvt_pk_bf16_f32 v0, v116, s0
	global_store_short v[12:13], v0, off
	v_add_co_u32_e32 v12, vcc, 0x10000, v12
	s_waitcnt vmcnt(40)
	s_nop 0
	v_addc_co_u32_e32 v13, vcc, 0, v13, vcc
	v_fma_f32 v116, v116, v109, v89
	v_cvt_pk_bf16_f32 v0, v116, s0
	global_store_short v[12:13], v0, off
	v_add_co_u32_e32 v12, vcc, 0x10000, v12
	s_waitcnt vmcnt(38)
	s_nop 0
	v_addc_co_u32_e32 v13, vcc, 0, v13, vcc
	v_fma_f32 v116, v116, v110, v90
	v_cvt_pk_bf16_f32 v0, v116, s0
	global_store_short v[12:13], v0, off
	v_add_co_u32_e32 v12, vcc, 0x10000, v12
	s_waitcnt vmcnt(36)
	s_nop 0
	v_addc_co_u32_e32 v13, vcc, 0, v13, vcc
	v_fma_f32 v116, v116, v111, v91
	v_cvt_pk_bf16_f32 v0, v116, s0
	global_store_short v[12:13], v0, off
	v_add_co_u32_e32 v12, vcc, 0x10000, v12
	s_waitcnt vmcnt(34)
	s_nop 0
	v_addc_co_u32_e32 v13, vcc, 0, v13, vcc
	v_fma_f32 v116, v116, v112, v92
	v_cvt_pk_bf16_f32 v0, v116, s0
	global_store_short v[12:13], v0, off
	v_add_co_u32_e32 v12, vcc, 0x10000, v12
	s_waitcnt vmcnt(32)
	s_nop 0
	v_addc_co_u32_e32 v13, vcc, 0, v13, vcc
	v_fma_f32 v116, v116, v113, v93
	v_cvt_pk_bf16_f32 v0, v116, s0
	global_store_short v[12:13], v0, off
	v_add_co_u32_e32 v12, vcc, 0x10000, v12
	s_waitcnt vmcnt(30)
	s_nop 0
	v_addc_co_u32_e32 v13, vcc, 0, v13, vcc
	v_fma_f32 v116, v116, v114, v94
	v_cvt_pk_bf16_f32 v0, v116, s0
	global_store_short v[12:13], v0, off
	v_add_co_u32_e32 v12, vcc, 0x10000, v12
	s_waitcnt vmcnt(28)
	s_nop 0
	v_addc_co_u32_e32 v13, vcc, 0, v13, vcc
	v_fma_f32 v116, v116, v115, v95
	v_cvt_pk_bf16_f32 v0, v116, s0
	global_store_short v[12:13], v0, off
	v_add_co_u32_e32 v12, vcc, 0x10000, v12
	s_waitcnt vmcnt(26)
	s_nop 0
	v_addc_co_u32_e32 v13, vcc, 0, v13, vcc
	v_fma_f32 v116, v116, v96, v76
	v_cvt_pk_bf16_f32 v0, v116, s0
	global_store_short v[12:13], v0, off
	v_add_co_u32_e32 v12, vcc, 0x10000, v12
	s_waitcnt vmcnt(24)
	s_nop 0
	v_addc_co_u32_e32 v13, vcc, 0, v13, vcc
	v_fma_f32 v116, v116, v97, v77
	v_cvt_pk_bf16_f32 v0, v116, s0
	global_store_short v[12:13], v0, off
	v_add_co_u32_e32 v12, vcc, 0x10000, v12
	s_waitcnt vmcnt(22)
	s_nop 0
	v_addc_co_u32_e32 v13, vcc, 0, v13, vcc
	v_fma_f32 v116, v116, v98, v78
	v_cvt_pk_bf16_f32 v0, v116, s0
	global_store_short v[12:13], v0, off
	v_add_co_u32_e32 v12, vcc, 0x10000, v12
	s_waitcnt vmcnt(20)
	s_nop 0
	v_addc_co_u32_e32 v13, vcc, 0, v13, vcc
	v_fma_f32 v116, v116, v99, v79
	s_mov_b32 s4, 0x1ffff
	v_cmp_lt_i32_e32 vcc, s4, v8
	s_or_b64 s[40:41], vcc, s[40:41]
	s_andn2_b64 exec, exec, s[40:41]
	s_cbranch_execnz .LBB0_44
